# wf GEMM residual epilogue rewritten: source loads in flight instead of 16 serialised load-wait-store round trips
# baseline (speedup 1.0000x reference)
; __device__ __forceinline__ unsigned cvt_pk_bf16(float lo, float hi) { unsigned r; asm("v_cvt_pk_bf16_f32 %0, %1, %2" : "=v"(r) : "v"(lo), "v"(hi)); return r; }
;     __device__ __forceinline__ void operator()(const Acc& acc, const Unit& u, int wr, int wc, int fr, int fq) const {
;     ...
;         const int r0 = wr * 64 + fr, col0 = u.pn * 256 + wc * 32 + 8 * fq; const float* gp = gate + (size_t)mb * 9216 + col0;
;         f32x4 gv[2][2];
; #pragma unroll
;         for (int bj = 0; bj < 2; ++bj)
; #pragma unroll
;             for (int n = 0; n < 2; ++n) gv[bj][n] = *(const f32x4*)(gp + bj * 128 + n * 4) * f;
; #pragma unroll
;         for (int ai = 0; ai < 2; ++ai)
; #pragma unroll
;             for (int m = 0; m < 4; ++m) { const size_t off = (size_t)(r0 + ai * 128 + m * 16) * D + col0;
; #pragma unroll
;                 for (int bj = 0; bj < 2; ++bj) { const size_t o2 = off + bj * 128; f32x4 s0, s1;
;                     if (SRC32) { s0 = *(const f32x4*)(sp32 + o2); s1 = *(const f32x4*)(sp32 + o2 + 4); }
;                     else { const u32x4 q = *(const u32x4*)(sp16 + o2); s0 = (f32x4){bf2f(q.x & 0xffffu), bf2f(q.x >> 16), bf2f(q.y & 0xffffu), bf2f(q.y >> 16)}; s1 = (f32x4){bf2f(q.z & 0xffffu), bf2f(q.z >> 16), bf2f(q.w & 0xffffu), bf2f(q.w >> 16)}; }
;                     const f32x4 v0 = s0 + gv[bj][0] * acc[ai][bj][m][0], v1 = s1 + gv[bj][1] * acc[ai][bj][m][1];
;                     if (DST32) { *(f32x4*)(dp32 + o2) = v0; *(f32x4*)(dp32 + o2 + 4) = v1; }
;                     else { u32x4 w; w.x = cvt_pk_bf16(v0.x, v0.y); w.y = cvt_pk_bf16(v0.z, v0.w); w.z = cvt_pk_bf16(v1.x, v1.y); w.w = cvt_pk_bf16(v1.z, v1.w); *(u32x4*)(dp16 + o2) = w; } } }
.LBB0_1742:
	s_add_i32 s23, s38, 0xffffff80
	s_and_b64 s[42:43], s[42:43], exec
	s_cselect_b32 s42, s38, s23
	s_ashr_i32 s43, s42, 31
	v_lshl_or_b32 v172, s39, 8, v175
	s_lshl_b64 s[38:39], s[40:41], 2
	s_add_u32 s38, s50, s38
	s_addc_u32 s39, s51, s39
	s_lshl_b64 s[42:43], s[42:43], 19
	s_add_u32 s40, s86, s42
	s_addc_u32 s41, s87, s43
	v_lshlrev_b32_e32 v184, 2, v172
	global_load_dwordx4 v[128:131], v184, s[38:39]
	global_load_dwordx4 v[124:127], v184, s[38:39] offset:16
	global_load_dwordx4 v[108:111], v184, s[38:39] offset:512
	global_load_dwordx4 v[104:107], v184, s[38:39] offset:528
	s_add_u32 s38, s72, s42
	s_addc_u32 s39, s73, s43
	v_add_lshl_u32 v185, v148, v172, 1
	global_load_dwordx4 v[192:195], v185, s[40:41]
	global_load_dwordx4 v[196:199], v185, s[40:41] offset:256
	v_add_lshl_u32 v184, v150, v172, 1
	global_load_dwordx4 v[200:203], v184, s[40:41]
	global_load_dwordx4 v[208:211], v184, s[40:41] offset:256
	v_add_lshl_u32 v185, v152, v172, 1
	global_load_dwordx4 v[212:215], v185, s[40:41]
	global_load_dwordx4 v[216:219], v185, s[40:41] offset:256
	v_add_lshl_u32 v184, v154, v172, 1
	global_load_dwordx4 v[220:223], v184, s[40:41]
	global_load_dwordx4 v[224:227], v184, s[40:41] offset:256
	v_add_lshl_u32 v185, v156, v172, 1
	global_load_dwordx4 v[228:231], v185, s[40:41]
	global_load_dwordx4 v[238:241], v185, s[40:41] offset:256
	v_add_lshl_u32 v184, v158, v172, 1
	global_load_dwordx4 v[242:245], v184, s[40:41]
	global_load_dwordx4 v[246:249], v184, s[40:41] offset:256
	s_waitcnt vmcnt(11)
	v_lshlrev_b32_e32 v180, 16, v192
	v_and_b32_e32 v181, 0xffff0000, v192
	v_lshlrev_b32_e32 v182, 16, v193
	v_and_b32_e32 v183, 0xffff0000, v193
	v_lshlrev_b32_e32 v192, 16, v194
	v_and_b32_e32 v193, 0xffff0000, v194
	v_lshlrev_b32_e32 v194, 16, v195
	v_and_b32_e32 v195, 0xffff0000, v195
	v_pk_fma_f32 v[140:141], v[140:141], v[128:129], v[180:181]
	v_pk_fma_f32 v[142:143], v[142:143], v[130:131], v[182:183]
	v_pk_fma_f32 v[136:137], v[136:137], v[124:125], v[192:193]
	v_pk_fma_f32 v[138:139], v[138:139], v[126:127], v[194:195]
	v_cvt_pk_bf16_f32 v140, v140, v141
	v_cvt_pk_bf16_f32 v141, v142, v143
	v_cvt_pk_bf16_f32 v142, v136, v137
	v_cvt_pk_bf16_f32 v143, v138, v139
	s_waitcnt vmcnt(10)
	v_lshlrev_b32_e32 v180, 16, v196
	v_and_b32_e32 v181, 0xffff0000, v196
	v_lshlrev_b32_e32 v182, 16, v197
	v_and_b32_e32 v183, 0xffff0000, v197
	v_lshlrev_b32_e32 v196, 16, v198
	v_and_b32_e32 v197, 0xffff0000, v198
	v_lshlrev_b32_e32 v198, 16, v199
	v_and_b32_e32 v199, 0xffff0000, v199
	v_pk_fma_f32 v[132:133], v[132:133], v[108:109], v[180:181]
	v_pk_fma_f32 v[134:135], v[134:135], v[110:111], v[182:183]
	v_pk_fma_f32 v[120:121], v[120:121], v[104:105], v[196:197]
	v_pk_fma_f32 v[122:123], v[122:123], v[106:107], v[198:199]
	v_cvt_pk_bf16_f32 v132, v132, v133
	v_cvt_pk_bf16_f32 v133, v134, v135
	v_cvt_pk_bf16_f32 v134, v120, v121
	v_cvt_pk_bf16_f32 v135, v122, v123
	s_waitcnt vmcnt(9)
	v_lshlrev_b32_e32 v180, 16, v200
	v_and_b32_e32 v181, 0xffff0000, v200
	v_lshlrev_b32_e32 v182, 16, v201
	v_and_b32_e32 v183, 0xffff0000, v201
	v_lshlrev_b32_e32 v200, 16, v202
	v_and_b32_e32 v201, 0xffff0000, v202
	v_lshlrev_b32_e32 v202, 16, v203
	v_and_b32_e32 v203, 0xffff0000, v203
	v_pk_fma_f32 v[116:117], v[116:117], v[128:129], v[180:181]
	v_pk_fma_f32 v[118:119], v[118:119], v[130:131], v[182:183]
	v_pk_fma_f32 v[112:113], v[112:113], v[124:125], v[200:201]
	v_pk_fma_f32 v[114:115], v[114:115], v[126:127], v[202:203]
	v_cvt_pk_bf16_f32 v116, v116, v117
	v_cvt_pk_bf16_f32 v117, v118, v119
	v_cvt_pk_bf16_f32 v118, v112, v113
	v_cvt_pk_bf16_f32 v119, v114, v115
	s_waitcnt vmcnt(8)
	v_lshlrev_b32_e32 v180, 16, v208
	v_and_b32_e32 v181, 0xffff0000, v208
	v_lshlrev_b32_e32 v182, 16, v209
	v_and_b32_e32 v183, 0xffff0000, v209
	v_lshlrev_b32_e32 v208, 16, v210
	v_and_b32_e32 v209, 0xffff0000, v210
	v_lshlrev_b32_e32 v210, 16, v211
	v_and_b32_e32 v211, 0xffff0000, v211
	v_pk_fma_f32 v[100:101], v[100:101], v[108:109], v[180:181]
	v_pk_fma_f32 v[102:103], v[102:103], v[110:111], v[182:183]
	v_pk_fma_f32 v[96:97], v[96:97], v[104:105], v[208:209]
	v_pk_fma_f32 v[98:99], v[98:99], v[106:107], v[210:211]
	v_cvt_pk_bf16_f32 v100, v100, v101
	v_cvt_pk_bf16_f32 v101, v102, v103
	v_cvt_pk_bf16_f32 v102, v96, v97
	v_cvt_pk_bf16_f32 v103, v98, v99
	v_add_lshl_u32 v185, v160, v172, 1
	global_load_dwordx4 v[192:195], v185, s[40:41]
	global_load_dwordx4 v[196:199], v185, s[40:41] offset:256
	v_add_lshl_u32 v184, v162, v172, 1
	global_load_dwordx4 v[200:203], v184, s[40:41]
	global_load_dwordx4 v[208:211], v184, s[40:41] offset:256
	s_waitcnt vmcnt(11)
	v_lshlrev_b32_e32 v180, 16, v212
	v_and_b32_e32 v181, 0xffff0000, v212
	v_lshlrev_b32_e32 v182, 16, v213
	v_and_b32_e32 v183, 0xffff0000, v213
	v_lshlrev_b32_e32 v212, 16, v214
	v_and_b32_e32 v213, 0xffff0000, v214
	v_lshlrev_b32_e32 v214, 16, v215
	v_and_b32_e32 v215, 0xffff0000, v215
	v_pk_fma_f32 v[92:93], v[92:93], v[128:129], v[180:181]
	v_pk_fma_f32 v[94:95], v[94:95], v[130:131], v[182:183]
	v_pk_fma_f32 v[88:89], v[88:89], v[124:125], v[212:213]
	v_pk_fma_f32 v[90:91], v[90:91], v[126:127], v[214:215]
	v_cvt_pk_bf16_f32 v92, v92, v93
	v_cvt_pk_bf16_f32 v93, v94, v95
	v_cvt_pk_bf16_f32 v94, v88, v89
	v_cvt_pk_bf16_f32 v95, v90, v91
	s_waitcnt vmcnt(10)
	v_lshlrev_b32_e32 v180, 16, v216
	v_and_b32_e32 v181, 0xffff0000, v216
	v_lshlrev_b32_e32 v182, 16, v217
	v_and_b32_e32 v183, 0xffff0000, v217
	v_lshlrev_b32_e32 v216, 16, v218
	v_and_b32_e32 v217, 0xffff0000, v218
	v_lshlrev_b32_e32 v218, 16, v219
	v_and_b32_e32 v219, 0xffff0000, v219
	v_pk_fma_f32 v[84:85], v[84:85], v[108:109], v[180:181]
	v_pk_fma_f32 v[86:87], v[86:87], v[110:111], v[182:183]
	v_pk_fma_f32 v[80:81], v[80:81], v[104:105], v[216:217]
	v_pk_fma_f32 v[82:83], v[82:83], v[106:107], v[218:219]
	v_cvt_pk_bf16_f32 v84, v84, v85
	v_cvt_pk_bf16_f32 v85, v86, v87
	v_cvt_pk_bf16_f32 v86, v80, v81
	v_cvt_pk_bf16_f32 v87, v82, v83
	s_waitcnt vmcnt(9)
; __device__ __forceinline__ unsigned cvt_pk_bf16(float lo, float hi) { unsigned r; asm("v_cvt_pk_bf16_f32 %0, %1, %2" : "=v"(r) : "v"(lo), "v"(hi)); return r; }
;     __device__ __forceinline__ void operator()(const Acc& acc, const Unit& u, int wr, int wc, int fr, int fq) const {
;     ...
;             for (int m = 0; m < 4; ++m) { const size_t off = (size_t)(r0 + ai * 128 + m * 16) * D + col0;
; #pragma unroll
;                 for (int bj = 0; bj < 2; ++bj) { const size_t o2 = off + bj * 128; f32x4 s0, s1;
;                     if (SRC32) { s0 = *(const f32x4*)(sp32 + o2); s1 = *(const f32x4*)(sp32 + o2 + 4); }
;                     else { const u32x4 q = *(const u32x4*)(sp16 + o2); s0 = (f32x4){bf2f(q.x & 0xffffu), bf2f(q.x >> 16), bf2f(q.y & 0xffffu), bf2f(q.y >> 16)}; s1 = (f32x4){bf2f(q.z & 0xffffu), bf2f(q.z >> 16), bf2f(q.w & 0xffffu), bf2f(q.w >> 16)}; }
;                     const f32x4 v0 = s0 + gv[bj][0] * acc[ai][bj][m][0], v1 = s1 + gv[bj][1] * acc[ai][bj][m][1];
;                     if (DST32) { *(f32x4*)(dp32 + o2) = v0; *(f32x4*)(dp32 + o2 + 4) = v1; }
;                     else { u32x4 w; w.x = cvt_pk_bf16(v0.x, v0.y); w.y = cvt_pk_bf16(v0.z, v0.w); w.z = cvt_pk_bf16(v1.x, v1.y); w.w = cvt_pk_bf16(v1.z, v1.w); *(u32x4*)(dp16 + o2) = w; } } }
	v_lshlrev_b32_e32 v180, 16, v220
	v_and_b32_e32 v181, 0xffff0000, v220
	v_lshlrev_b32_e32 v182, 16, v221
	v_and_b32_e32 v183, 0xffff0000, v221
	v_lshlrev_b32_e32 v220, 16, v222
	v_and_b32_e32 v221, 0xffff0000, v222
	v_lshlrev_b32_e32 v222, 16, v223
	v_and_b32_e32 v223, 0xffff0000, v223
	v_pk_fma_f32 v[76:77], v[76:77], v[128:129], v[180:181]
	v_pk_fma_f32 v[78:79], v[78:79], v[130:131], v[182:183]
	v_pk_fma_f32 v[72:73], v[72:73], v[124:125], v[220:221]
	v_pk_fma_f32 v[74:75], v[74:75], v[126:127], v[222:223]
	v_cvt_pk_bf16_f32 v76, v76, v77
	v_cvt_pk_bf16_f32 v77, v78, v79
	v_cvt_pk_bf16_f32 v78, v72, v73
	v_cvt_pk_bf16_f32 v79, v74, v75
	s_waitcnt vmcnt(8)
	v_lshlrev_b32_e32 v180, 16, v224
	v_and_b32_e32 v181, 0xffff0000, v224
	v_lshlrev_b32_e32 v182, 16, v225
	v_and_b32_e32 v183, 0xffff0000, v225
	v_lshlrev_b32_e32 v224, 16, v226
	v_and_b32_e32 v225, 0xffff0000, v226
	v_lshlrev_b32_e32 v226, 16, v227
	v_and_b32_e32 v227, 0xffff0000, v227
	v_pk_fma_f32 v[68:69], v[68:69], v[108:109], v[180:181]
	v_pk_fma_f32 v[70:71], v[70:71], v[110:111], v[182:183]
	v_pk_fma_f32 v[64:65], v[64:65], v[104:105], v[224:225]
	v_pk_fma_f32 v[66:67], v[66:67], v[106:107], v[226:227]
	v_cvt_pk_bf16_f32 v68, v68, v69
	v_cvt_pk_bf16_f32 v69, v70, v71
	v_cvt_pk_bf16_f32 v70, v64, v65
	v_cvt_pk_bf16_f32 v71, v66, v67
	s_waitcnt vmcnt(7)
	v_lshlrev_b32_e32 v180, 16, v228
	v_and_b32_e32 v181, 0xffff0000, v228
	v_lshlrev_b32_e32 v182, 16, v229
	v_and_b32_e32 v183, 0xffff0000, v229
	v_lshlrev_b32_e32 v228, 16, v230
	v_and_b32_e32 v229, 0xffff0000, v230
	v_lshlrev_b32_e32 v230, 16, v231
	v_and_b32_e32 v231, 0xffff0000, v231
	v_pk_fma_f32 v[60:61], v[60:61], v[128:129], v[180:181]
	v_pk_fma_f32 v[62:63], v[62:63], v[130:131], v[182:183]
	v_pk_fma_f32 v[56:57], v[56:57], v[124:125], v[228:229]
	v_pk_fma_f32 v[58:59], v[58:59], v[126:127], v[230:231]
	v_cvt_pk_bf16_f32 v60, v60, v61
	v_cvt_pk_bf16_f32 v61, v62, v63
	v_cvt_pk_bf16_f32 v62, v56, v57
	v_cvt_pk_bf16_f32 v63, v58, v59
	s_waitcnt vmcnt(6)
	v_lshlrev_b32_e32 v180, 16, v238
	v_and_b32_e32 v181, 0xffff0000, v238
	v_lshlrev_b32_e32 v182, 16, v239
	v_and_b32_e32 v183, 0xffff0000, v239
	v_lshlrev_b32_e32 v238, 16, v240
	v_and_b32_e32 v239, 0xffff0000, v240
	v_lshlrev_b32_e32 v240, 16, v241
	v_and_b32_e32 v241, 0xffff0000, v241
	v_pk_fma_f32 v[52:53], v[52:53], v[108:109], v[180:181]
	v_pk_fma_f32 v[54:55], v[54:55], v[110:111], v[182:183]
	v_pk_fma_f32 v[48:49], v[48:49], v[104:105], v[238:239]
	v_pk_fma_f32 v[50:51], v[50:51], v[106:107], v[240:241]
	v_cvt_pk_bf16_f32 v52, v52, v53
	v_cvt_pk_bf16_f32 v53, v54, v55
	v_cvt_pk_bf16_f32 v54, v48, v49
	v_cvt_pk_bf16_f32 v55, v50, v51
	s_waitcnt vmcnt(5)
	v_lshlrev_b32_e32 v180, 16, v242
	v_and_b32_e32 v181, 0xffff0000, v242
	v_lshlrev_b32_e32 v182, 16, v243
	v_and_b32_e32 v183, 0xffff0000, v243
	v_lshlrev_b32_e32 v242, 16, v244
	v_and_b32_e32 v243, 0xffff0000, v244
	v_lshlrev_b32_e32 v244, 16, v245
	v_and_b32_e32 v245, 0xffff0000, v245
	v_pk_fma_f32 v[44:45], v[44:45], v[128:129], v[180:181]
	v_pk_fma_f32 v[46:47], v[46:47], v[130:131], v[182:183]
	v_pk_fma_f32 v[40:41], v[40:41], v[124:125], v[242:243]
	v_pk_fma_f32 v[42:43], v[42:43], v[126:127], v[244:245]
	v_cvt_pk_bf16_f32 v44, v44, v45
	v_cvt_pk_bf16_f32 v45, v46, v47
	v_cvt_pk_bf16_f32 v46, v40, v41
	v_cvt_pk_bf16_f32 v47, v42, v43
	s_waitcnt vmcnt(4)
	v_lshlrev_b32_e32 v180, 16, v246
	v_and_b32_e32 v181, 0xffff0000, v246
	v_lshlrev_b32_e32 v182, 16, v247
	v_and_b32_e32 v183, 0xffff0000, v247
	v_lshlrev_b32_e32 v246, 16, v248
	v_and_b32_e32 v247, 0xffff0000, v248
	v_lshlrev_b32_e32 v248, 16, v249
	v_and_b32_e32 v249, 0xffff0000, v249
	v_pk_fma_f32 v[36:37], v[36:37], v[108:109], v[180:181]
	v_pk_fma_f32 v[38:39], v[38:39], v[110:111], v[182:183]
	v_pk_fma_f32 v[32:33], v[32:33], v[104:105], v[246:247]
	v_pk_fma_f32 v[34:35], v[34:35], v[106:107], v[248:249]
	v_cvt_pk_bf16_f32 v36, v36, v37
	v_cvt_pk_bf16_f32 v37, v38, v39
	v_cvt_pk_bf16_f32 v38, v32, v33
	v_cvt_pk_bf16_f32 v39, v34, v35
	s_waitcnt vmcnt(3)
; __device__ __forceinline__ unsigned cvt_pk_bf16(float lo, float hi) { unsigned r; asm("v_cvt_pk_bf16_f32 %0, %1, %2" : "=v"(r) : "v"(lo), "v"(hi)); return r; }
;     __device__ __forceinline__ void operator()(const Acc& acc, const Unit& u, int wr, int wc, int fr, int fq) const {
;     ...
;             for (int m = 0; m < 4; ++m) { const size_t off = (size_t)(r0 + ai * 128 + m * 16) * D + col0;
; #pragma unroll
;                 for (int bj = 0; bj < 2; ++bj) { const size_t o2 = off + bj * 128; f32x4 s0, s1;
;                     if (SRC32) { s0 = *(const f32x4*)(sp32 + o2); s1 = *(const f32x4*)(sp32 + o2 + 4); }
;                     else { const u32x4 q = *(const u32x4*)(sp16 + o2); s0 = (f32x4){bf2f(q.x & 0xffffu), bf2f(q.x >> 16), bf2f(q.y & 0xffffu), bf2f(q.y >> 16)}; s1 = (f32x4){bf2f(q.z & 0xffffu), bf2f(q.z >> 16), bf2f(q.w & 0xffffu), bf2f(q.w >> 16)}; }
;                     const f32x4 v0 = s0 + gv[bj][0] * acc[ai][bj][m][0], v1 = s1 + gv[bj][1] * acc[ai][bj][m][1];
;                     if (DST32) { *(f32x4*)(dp32 + o2) = v0; *(f32x4*)(dp32 + o2 + 4) = v1; }
;                     else { u32x4 w; w.x = cvt_pk_bf16(v0.x, v0.y); w.y = cvt_pk_bf16(v0.z, v0.w); w.z = cvt_pk_bf16(v1.x, v1.y); w.w = cvt_pk_bf16(v1.z, v1.w); *(u32x4*)(dp16 + o2) = w; } } }
	v_lshlrev_b32_e32 v180, 16, v192
	v_and_b32_e32 v181, 0xffff0000, v192
	v_lshlrev_b32_e32 v182, 16, v193
	v_and_b32_e32 v183, 0xffff0000, v193
	v_lshlrev_b32_e32 v192, 16, v194
	v_and_b32_e32 v193, 0xffff0000, v194
	v_lshlrev_b32_e32 v194, 16, v195
	v_and_b32_e32 v195, 0xffff0000, v195
	v_pk_fma_f32 v[28:29], v[28:29], v[128:129], v[180:181]
	v_pk_fma_f32 v[30:31], v[30:31], v[130:131], v[182:183]
	v_pk_fma_f32 v[24:25], v[24:25], v[124:125], v[192:193]
	v_pk_fma_f32 v[26:27], v[26:27], v[126:127], v[194:195]
	v_cvt_pk_bf16_f32 v28, v28, v29
	v_cvt_pk_bf16_f32 v29, v30, v31
	v_cvt_pk_bf16_f32 v30, v24, v25
	v_cvt_pk_bf16_f32 v31, v26, v27
	s_waitcnt vmcnt(2)
	v_lshlrev_b32_e32 v180, 16, v196
	v_and_b32_e32 v181, 0xffff0000, v196
	v_lshlrev_b32_e32 v182, 16, v197
	v_and_b32_e32 v183, 0xffff0000, v197
	v_lshlrev_b32_e32 v196, 16, v198
	v_and_b32_e32 v197, 0xffff0000, v198
	v_lshlrev_b32_e32 v198, 16, v199
	v_and_b32_e32 v199, 0xffff0000, v199
	v_pk_fma_f32 v[20:21], v[20:21], v[108:109], v[180:181]
	v_pk_fma_f32 v[22:23], v[22:23], v[110:111], v[182:183]
	v_pk_fma_f32 v[16:17], v[16:17], v[104:105], v[196:197]
	v_pk_fma_f32 v[18:19], v[18:19], v[106:107], v[198:199]
	v_cvt_pk_bf16_f32 v20, v20, v21
	v_cvt_pk_bf16_f32 v21, v22, v23
	v_cvt_pk_bf16_f32 v22, v16, v17
	v_cvt_pk_bf16_f32 v23, v18, v19
	s_waitcnt vmcnt(1)
	v_lshlrev_b32_e32 v180, 16, v200
	v_and_b32_e32 v181, 0xffff0000, v200
	v_lshlrev_b32_e32 v182, 16, v201
	v_and_b32_e32 v183, 0xffff0000, v201
	v_lshlrev_b32_e32 v200, 16, v202
	v_and_b32_e32 v201, 0xffff0000, v202
	v_lshlrev_b32_e32 v202, 16, v203
	v_and_b32_e32 v203, 0xffff0000, v203
	v_pk_fma_f32 v[12:13], v[12:13], v[128:129], v[180:181]
	v_pk_fma_f32 v[14:15], v[14:15], v[130:131], v[182:183]
	v_pk_fma_f32 v[8:9], v[8:9], v[124:125], v[200:201]
	v_pk_fma_f32 v[10:11], v[10:11], v[126:127], v[202:203]
	v_cvt_pk_bf16_f32 v12, v12, v13
	v_cvt_pk_bf16_f32 v13, v14, v15
	v_cvt_pk_bf16_f32 v14, v8, v9
	v_cvt_pk_bf16_f32 v15, v10, v11
	s_waitcnt vmcnt(0)
	v_lshlrev_b32_e32 v180, 16, v208
	v_and_b32_e32 v181, 0xffff0000, v208
	v_lshlrev_b32_e32 v182, 16, v209
	v_and_b32_e32 v183, 0xffff0000, v209
	v_lshlrev_b32_e32 v208, 16, v210
	v_and_b32_e32 v209, 0xffff0000, v210
	v_lshlrev_b32_e32 v210, 16, v211
	v_and_b32_e32 v211, 0xffff0000, v211
	v_pk_fma_f32 v[4:5], v[4:5], v[108:109], v[180:181]
	v_pk_fma_f32 v[6:7], v[6:7], v[110:111], v[182:183]
	v_pk_fma_f32 v[0:1], v[0:1], v[104:105], v[208:209]
	v_pk_fma_f32 v[2:3], v[2:3], v[106:107], v[210:211]
	v_cvt_pk_bf16_f32 v4, v4, v5
	v_cvt_pk_bf16_f32 v5, v6, v7
	v_cvt_pk_bf16_f32 v6, v0, v1
	v_cvt_pk_bf16_f32 v7, v2, v3
	v_add_lshl_u32 v184, v148, v172, 1
	global_store_dwordx4 v184, v[140:143], s[38:39]
	global_store_dwordx4 v184, v[132:135], s[38:39] offset:256
	v_add_lshl_u32 v185, v150, v172, 1
	global_store_dwordx4 v185, v[116:119], s[38:39]
	global_store_dwordx4 v185, v[100:103], s[38:39] offset:256
	v_add_lshl_u32 v184, v152, v172, 1
	global_store_dwordx4 v184, v[92:95], s[38:39]
	global_store_dwordx4 v184, v[84:87], s[38:39] offset:256
	v_add_lshl_u32 v185, v154, v172, 1
	global_store_dwordx4 v185, v[76:79], s[38:39]
	global_store_dwordx4 v185, v[68:71], s[38:39] offset:256
	v_add_lshl_u32 v184, v156, v172, 1
	global_store_dwordx4 v184, v[60:63], s[38:39]
	global_store_dwordx4 v184, v[52:55], s[38:39] offset:256
	v_add_lshl_u32 v185, v158, v172, 1
	global_store_dwordx4 v185, v[44:47], s[38:39]
	global_store_dwordx4 v185, v[36:39], s[38:39] offset:256
	v_add_lshl_u32 v184, v160, v172, 1
	global_store_dwordx4 v184, v[28:31], s[38:39]
	global_store_dwordx4 v184, v[20:23], s[38:39] offset:256
	v_add_lshl_u32 v185, v162, v172, 1
	global_store_dwordx4 v185, v[12:15], s[38:39]
	global_store_dwordx4 v185, v[4:7], s[38:39] offset:256
	s_andn2_b64 vcc, exec, s[6:7]
	s_mov_b64 s[6:7], -1
	s_cbranch_vccnz .LBB0_1729
	s_andn2_b64 vcc, exec, s[0:1]
	s_cbranch_vccnz .LBB0_1728
	s_barrier
	s_branch .LBB0_1728
